# P1 pair epilogue: the four 32-B segments of each 128-B output line are now stored back to back (loop order t, mi, ni, kp)
# speedup vs baseline: 1.0105x; 1.0063x over previous
; DI unsigned pk2(float a, float b) { f32x2 v = {a, b}; return __builtin_bit_cast(unsigned, __builtin_convertvector(v, bf2_t)); }
; DI void store_rowmajor(u16* dst, const f32x16& a, int h, float sc) {
; #pragma unroll
;   for (int kp = 0; kp < 2; ++kp) {
;     const int g = 2 * kp;
;     unsigned ax = pk2(a[4 * g] * sc, a[4 * g + 1] * sc), ay = pk2(a[4 * g + 2] * sc, a[4 * g + 3] * sc);
;     unsigned bx = pk2(a[4 * g + 4] * sc, a[4 * g + 5] * sc), by = pk2(a[4 * g + 6] * sc, a[4 * g + 7] * sc);
;     const u32x2 rx = __builtin_amdgcn_permlane32_swap(ax, bx, false, false);
;     const u32x2 ry = __builtin_amdgcn_permlane32_swap(ay, by, false, false);
;     const u32x4 v = {rx[0], ry[0], rx[1], ry[1]};
;     *(u32x4*)(dst + 8 * (g + h)) = v;
;   }
; }
; DI void inproj_tile(const Params& p, int l, int mt, int nt, char* lds) {
;     ...
;     gemm_tile<true>(A, DM, Bw, DM, DM, lds, [&](int mi, int ni, const f32x16& a) {
;       const int tok = m0 + wm * 64 + mi * 32 + r;
;       store_rowmajor(p.H + (size_t)tok * LDH + nt * 128 + wn * 64 + ni * 32, a, h, 1.f);
.Lpp_nopf:
	s_nop 7
	s_nop 7
	v_cvt_pk_bf16_f32 v224, v4, v5
	v_cvt_pk_bf16_f32 v225, v6, v7
	v_cvt_pk_bf16_f32 v226, v8, v9
	v_cvt_pk_bf16_f32 v227, v10, v11
	s_nop 1
	v_permlane32_swap_b32_e32 v224, v226
	v_permlane32_swap_b32_e32 v225, v227
	s_nop 0
	global_store_dwordx4 v218, v[224:227], s[8:9]
	v_cvt_pk_bf16_f32 v228, v12, v13
	v_cvt_pk_bf16_f32 v229, v14, v15
	v_cvt_pk_bf16_f32 v230, v16, v17
	v_cvt_pk_bf16_f32 v231, v18, v19
	s_nop 1
	v_permlane32_swap_b32_e32 v228, v230
	v_permlane32_swap_b32_e32 v229, v231
	s_nop 0
	global_store_dwordx4 v218, v[228:231], s[8:9] offset:32
	v_cvt_pk_bf16_f32 v224, v20, v21
	v_cvt_pk_bf16_f32 v225, v22, v23
	v_cvt_pk_bf16_f32 v226, v24, v25
	v_cvt_pk_bf16_f32 v227, v26, v27
	s_nop 1
	v_permlane32_swap_b32_e32 v224, v226
	v_permlane32_swap_b32_e32 v225, v227
	s_nop 0
	global_store_dwordx4 v218, v[224:227], s[8:9] offset:64
	v_cvt_pk_bf16_f32 v228, v28, v29
	v_cvt_pk_bf16_f32 v229, v30, v31
	v_cvt_pk_bf16_f32 v230, v32, v33
	v_cvt_pk_bf16_f32 v231, v34, v35
	s_nop 1
	v_permlane32_swap_b32_e32 v228, v230
	v_permlane32_swap_b32_e32 v229, v231
	s_nop 0
	global_store_dwordx4 v218, v[228:231], s[8:9] offset:96
	v_cvt_pk_bf16_f32 v224, v68, v69
	v_cvt_pk_bf16_f32 v225, v70, v71
	v_cvt_pk_bf16_f32 v226, v72, v73
	v_cvt_pk_bf16_f32 v227, v74, v75
	s_nop 1
	v_permlane32_swap_b32_e32 v224, v226
	v_permlane32_swap_b32_e32 v225, v227
	s_nop 0
	global_store_dwordx4 v219, v[224:227], s[8:9]
	v_cvt_pk_bf16_f32 v228, v76, v77
	v_cvt_pk_bf16_f32 v229, v78, v79
	v_cvt_pk_bf16_f32 v230, v80, v81
	v_cvt_pk_bf16_f32 v231, v82, v83
	s_nop 1
	v_permlane32_swap_b32_e32 v228, v230
	v_permlane32_swap_b32_e32 v229, v231
	s_nop 0
	global_store_dwordx4 v219, v[228:231], s[8:9] offset:32
	v_cvt_pk_bf16_f32 v224, v84, v85
	v_cvt_pk_bf16_f32 v225, v86, v87
	v_cvt_pk_bf16_f32 v226, v88, v89
	v_cvt_pk_bf16_f32 v227, v90, v91
	s_nop 1
	v_permlane32_swap_b32_e32 v224, v226
	v_permlane32_swap_b32_e32 v225, v227
	s_nop 0
	global_store_dwordx4 v219, v[224:227], s[8:9] offset:64
	v_cvt_pk_bf16_f32 v228, v92, v93
	v_cvt_pk_bf16_f32 v229, v94, v95
	v_cvt_pk_bf16_f32 v230, v96, v97
	v_cvt_pk_bf16_f32 v231, v98, v99
	s_nop 1
	v_permlane32_swap_b32_e32 v228, v230
	v_permlane32_swap_b32_e32 v229, v231
	s_nop 0
	global_store_dwordx4 v219, v[228:231], s[8:9] offset:96
	v_cvt_pk_bf16_f32 v224, v36, v37
	v_cvt_pk_bf16_f32 v225, v38, v39
	v_cvt_pk_bf16_f32 v226, v40, v41
	v_cvt_pk_bf16_f32 v227, v42, v43
	s_nop 1
	v_permlane32_swap_b32_e32 v224, v226
	v_permlane32_swap_b32_e32 v225, v227
	s_nop 0
	global_store_dwordx4 v218, v[224:227], s[8:9] offset:256
	v_cvt_pk_bf16_f32 v228, v44, v45
	v_cvt_pk_bf16_f32 v229, v46, v47
	v_cvt_pk_bf16_f32 v230, v48, v49
	v_cvt_pk_bf16_f32 v231, v50, v51
	s_nop 1
	v_permlane32_swap_b32_e32 v228, v230
	v_permlane32_swap_b32_e32 v229, v231
	s_nop 0
	global_store_dwordx4 v218, v[228:231], s[8:9] offset:288
	v_cvt_pk_bf16_f32 v224, v52, v53
	v_cvt_pk_bf16_f32 v225, v54, v55
	v_cvt_pk_bf16_f32 v226, v56, v57
	v_cvt_pk_bf16_f32 v227, v58, v59
	s_nop 1
	v_permlane32_swap_b32_e32 v224, v226
	v_permlane32_swap_b32_e32 v225, v227
	s_nop 0
	global_store_dwordx4 v218, v[224:227], s[8:9] offset:320
	v_cvt_pk_bf16_f32 v228, v60, v61
	v_cvt_pk_bf16_f32 v229, v62, v63
	v_cvt_pk_bf16_f32 v230, v64, v65
	v_cvt_pk_bf16_f32 v231, v66, v67
	s_nop 1
	v_permlane32_swap_b32_e32 v228, v230
	v_permlane32_swap_b32_e32 v229, v231
	s_nop 0
	global_store_dwordx4 v218, v[228:231], s[8:9] offset:352
	v_cvt_pk_bf16_f32 v224, v100, v101
	v_cvt_pk_bf16_f32 v225, v102, v103
	v_cvt_pk_bf16_f32 v226, v104, v105
	v_cvt_pk_bf16_f32 v227, v106, v107
	s_nop 1
	v_permlane32_swap_b32_e32 v224, v226
	v_permlane32_swap_b32_e32 v225, v227
	s_nop 0
	global_store_dwordx4 v219, v[224:227], s[8:9] offset:256
	v_cvt_pk_bf16_f32 v228, v108, v109
	v_cvt_pk_bf16_f32 v229, v110, v111
	v_cvt_pk_bf16_f32 v230, v112, v113
	v_cvt_pk_bf16_f32 v231, v114, v115
	s_nop 1
	v_permlane32_swap_b32_e32 v228, v230
	v_permlane32_swap_b32_e32 v229, v231
	s_nop 0
	global_store_dwordx4 v219, v[228:231], s[8:9] offset:288
	v_cvt_pk_bf16_f32 v224, v116, v117
	v_cvt_pk_bf16_f32 v225, v118, v119
	v_cvt_pk_bf16_f32 v226, v120, v121
	v_cvt_pk_bf16_f32 v227, v122, v123
	s_nop 1
	v_permlane32_swap_b32_e32 v224, v226
	v_permlane32_swap_b32_e32 v225, v227
	s_nop 0
	global_store_dwordx4 v219, v[224:227], s[8:9] offset:320
	v_cvt_pk_bf16_f32 v228, v124, v125
	v_cvt_pk_bf16_f32 v229, v126, v127
	v_cvt_pk_bf16_f32 v230, v128, v129
	v_cvt_pk_bf16_f32 v231, v130, v131
	s_nop 1
	v_permlane32_swap_b32_e32 v228, v230
	v_permlane32_swap_b32_e32 v229, v231
	s_nop 0
	global_store_dwordx4 v219, v[228:231], s[8:9] offset:352
	s_branch .LBB0_323
